# S5 pass 2: workgroup barriers replaced by per-wave-pair LDS flag handshakes (forward/backward waves of one group sync only with each other)
# speedup vs baseline: 1.0049x; 1.0049x over previous
.Lp8_fwd:
	v_lshlrev_b32_e32 v4, 11, v3
	v_lshl_add_u32 v4, v1, 4, v4
	v_lshlrev_b32_e32 v5, 5, v0
	v_lshl_add_u32 v5, v1, 4, v5
	v_lshrrev_b32_e32 v6, 1, v0
	v_lshlrev_b32_e32 v6, 3, v6
	v_mov_b32_e32 v9, 0x420000
	v_mul_lo_u32 v7, v1, v9
	v_lshl_add_u32 v7, v0, 2, v7
	s_mul_i32 s10, s95, 0x2100
	v_lshl_add_u32 v9, v1, 7, v0
	v_lshlrev_b32_e32 v9, 4, v9
	v_add_u32_e32 v84, s10, v9
	v_lshrrev_b32_e32 v9, 2, v93
	v_lshl_add_u32 v9, v94, 3, v9
	v_lshlrev_b32_e32 v9, 4, v9
	v_and_b32_e32 v10, 1, v93
	v_lshl_add_u32 v9, v10, 3, v9
	v_bfe_u32 v10, v93, 1, 1
	v_mov_b32_e32 v85, 0x1040
	v_mul_lo_u32 v10, v10, v85
	v_add3_u32 v85, v9, v10, s10
	v_lshlrev_b32_e32 v86, 8, v93
	v_lshl_add_u32 v86, v94, 4, v86
	s_lshl_b32 s10, s95, 13
	s_add_i32 s10, s10, 0x10800
	v_lshlrev_b32_e32 v9, 6, v95
	v_lshl_add_u32 v9, v94, 4, v9
	v_add_u32_e32 v87, s10, v9
	v_lshrrev_b32_e32 v93, 7, v204
	v_bfe_u32 v94, v204, 1, 6
	v_and_b32_e32 v95, 1, v204
	v_lshlrev_b32_e32 v9, 14, v93
	v_lshl_add_u32 v9, v94, 6, v9
	v_lshl_add_u32 v9, v95, 5, v9
	v_add_u32_e32 v88, 0x10800, v9
	v_lshlrev_b32_e32 v9, 11, v94
	v_lshl_add_u32 v9, v93, 5, v9
	v_lshl_add_u32 v89, v95, 4, v9
	v_lshlrev_b32_e32 v9, 6, v93
	v_lshl_add_u32 v90, v95, 5, v9
	v_and_b32_e32 v9, 1, v0
	v_mov_b32_e32 v10, 0x80000000
	v_cmp_eq_u32_e32 vcc, 0, v9
	s_nop 3
	v_cndmask_b32_e32 v8, 0, v10, vcc
	s_lshl_b32 s10, s95, 2
	s_add_i32 s10, s10, 0x20800
	v_mov_b32_e32 v202, s10
	s_xor_b32 s10, s10, 4
	v_mov_b32_e32 v203, s10
	v_mov_b32_e32 v230, 0
	ds_write_b32 v202, v230
	ds_write_b32 v202, v230 offset:32
	s_mov_b32 s85, 0
	s_waitcnt lgkmcnt(0)
	s_barrier
	s_mov_b32 s27, -1
	s_mov_b32 s5, s8
	s_mov_b32 s35, 1
	s_branch .Lp8_prefetch

.Lp8_top_body:
	s_cmp_eq_u32 s85, 0
	s_cbranch_scc1 .Lp8_poll2_done
	s_mov_b32 vcc_lo, 0
.Lp8_poll2:
	s_add_u32 vcc_lo, vcc_lo, 1
	s_cmpk_gt_u32 vcc_lo, 0x7d0
	s_cbranch_scc1 .Lp8_poll2_done
	ds_read_b32 v230, v203 offset:32
	s_waitcnt lgkmcnt(0)
	s_nop 0
	v_readfirstlane_b32 s94, v230
	s_nop 3
	s_cmp_ge_u32 s94, s85
	s_cbranch_scc1 .Lp8_poll2_done
	s_sleep 1
	s_branch .Lp8_poll2
.Lp8_poll2_done:
	s_add_i32 s85, s85, 1
	v_mov_b64_e32 v[52:53], v[68:69]
	v_mov_b64_e32 v[54:55], v[70:71]
	v_mov_b64_e32 v[56:57], v[72:73]
	v_mov_b64_e32 v[58:59], v[74:75]
	v_mov_b64_e32 v[60:61], v[76:77]
	v_mov_b64_e32 v[62:63], v[78:79]
	v_mov_b64_e32 v[64:65], v[80:81]
	v_mov_b64_e32 v[66:67], v[82:83]
	v_mov_b32_e32 v12, v28
	v_mov_b32_e32 v13, v29
	v_mov_b32_e32 v14, v30
	v_mov_b32_e32 v15, v31
	s_mov_b32 s4, s5
	s_add_i32 s5, s5, s9
	s_cmpk_gt_u32 s5, 0x83f
	s_cbranch_scc1 .Lp8_compute

.Lp8_have_g:
	s_cmp_lt_u32 s6, 4
	s_mov_b32 s10, 0x80000
	s_cselect_b32 s84, s10, 0x1000000
	s_movk_i32 s10, 0x4000
	s_cselect_b32 s83, s10, 0xffffff00
	s_lshl_b32 s10, s6, 6
	s_add_i32 s83, s83, s10
	s_lshl_b32 s83, s83, 11
	s_lshl_b32 s10, s7, 7
	s_add_i32 s83, s83, s10
	v_add_u32_e32 v91, s83, v89
	v_add_u32_e32 v92, s84, v91
	global_load_dwordx4 v[214:217], v91, s[36:37]
	global_load_dwordx4 v[218:221], v92, s[36:37]
	v_mfma_f32_32x32x16_f16 v[96:111], v[52:55], v[36:39], 0
	v_mfma_f32_32x32x16_f16 v[112:127], v[52:55], v[40:43], 0
	v_mfma_f32_32x32x16_f16 v[128:143], v[52:55], v[44:47], 0
	v_mfma_f32_32x32x16_f16 v[144:159], v[52:55], v[48:51], 0
	s_nop 15
	v_fma_f32 v16, v20, v12, v96
	v_fma_f32 v17, v21, v13, v112
	v_fma_f32 v18, v22, v14, v128
	v_fma_f32 v19, v23, v15, v144
	v_fmac_f32_dpp v16, v12, v24 quad_perm:[1,0,3,2] row_mask:0xf bank_mask:0xf
	v_fmac_f32_dpp v17, v13, v25 quad_perm:[1,0,3,2] row_mask:0xf bank_mask:0xf
	v_fmac_f32_dpp v18, v14, v26 quad_perm:[1,0,3,2] row_mask:0xf bank_mask:0xf
	v_fmac_f32_dpp v19, v15, v27 quad_perm:[1,0,3,2] row_mask:0xf bank_mask:0xf
	v_fma_f32 v12, v20, v16, v97
	v_fma_f32 v13, v21, v17, v113
	v_fma_f32 v14, v22, v18, v129
	v_fma_f32 v15, v23, v19, v145
	v_fmac_f32_dpp v12, v16, v24 quad_perm:[1,0,3,2] row_mask:0xf bank_mask:0xf
	v_fmac_f32_dpp v13, v17, v25 quad_perm:[1,0,3,2] row_mask:0xf bank_mask:0xf
	v_fmac_f32_dpp v14, v18, v26 quad_perm:[1,0,3,2] row_mask:0xf bank_mask:0xf
	v_fmac_f32_dpp v15, v19, v27 quad_perm:[1,0,3,2] row_mask:0xf bank_mask:0xf
	v_cvt_pk_f16_f32 v178, v16, v12
	v_cvt_pk_f16_f32 v182, v17, v13
	v_cvt_pk_f16_f32 v186, v18, v14
	v_cvt_pk_f16_f32 v190, v19, v15
	v_fma_f32 v16, v20, v12, v98
	v_fma_f32 v17, v21, v13, v114
	v_fma_f32 v18, v22, v14, v130
	v_fma_f32 v19, v23, v15, v146
	v_fmac_f32_dpp v16, v12, v24 quad_perm:[1,0,3,2] row_mask:0xf bank_mask:0xf
	v_fmac_f32_dpp v17, v13, v25 quad_perm:[1,0,3,2] row_mask:0xf bank_mask:0xf
	v_fmac_f32_dpp v18, v14, v26 quad_perm:[1,0,3,2] row_mask:0xf bank_mask:0xf
	v_fmac_f32_dpp v19, v15, v27 quad_perm:[1,0,3,2] row_mask:0xf bank_mask:0xf
	v_fma_f32 v12, v20, v16, v99
	v_fma_f32 v13, v21, v17, v115
	v_fma_f32 v14, v22, v18, v131
	v_fma_f32 v15, v23, v19, v147
	v_fmac_f32_dpp v12, v16, v24 quad_perm:[1,0,3,2] row_mask:0xf bank_mask:0xf
	v_fmac_f32_dpp v13, v17, v25 quad_perm:[1,0,3,2] row_mask:0xf bank_mask:0xf
	v_fmac_f32_dpp v14, v18, v26 quad_perm:[1,0,3,2] row_mask:0xf bank_mask:0xf
	v_fmac_f32_dpp v15, v19, v27 quad_perm:[1,0,3,2] row_mask:0xf bank_mask:0xf
	v_cvt_pk_f16_f32 v179, v16, v12
	v_cvt_pk_f16_f32 v183, v17, v13
	v_cvt_pk_f16_f32 v187, v18, v14
	v_cvt_pk_f16_f32 v191, v19, v15
	v_fma_f32 v16, v20, v12, v100
	v_fma_f32 v17, v21, v13, v116
	v_fma_f32 v18, v22, v14, v132
	v_fma_f32 v19, v23, v15, v148
	v_fmac_f32_dpp v16, v12, v24 quad_perm:[1,0,3,2] row_mask:0xf bank_mask:0xf
	v_fmac_f32_dpp v17, v13, v25 quad_perm:[1,0,3,2] row_mask:0xf bank_mask:0xf
	v_fmac_f32_dpp v18, v14, v26 quad_perm:[1,0,3,2] row_mask:0xf bank_mask:0xf
	v_fmac_f32_dpp v19, v15, v27 quad_perm:[1,0,3,2] row_mask:0xf bank_mask:0xf
	v_fma_f32 v12, v20, v16, v101
	v_fma_f32 v13, v21, v17, v117
	v_fma_f32 v14, v22, v18, v133
	v_fma_f32 v15, v23, v19, v149
	v_fmac_f32_dpp v12, v16, v24 quad_perm:[1,0,3,2] row_mask:0xf bank_mask:0xf
	v_fmac_f32_dpp v13, v17, v25 quad_perm:[1,0,3,2] row_mask:0xf bank_mask:0xf
	v_fmac_f32_dpp v14, v18, v26 quad_perm:[1,0,3,2] row_mask:0xf bank_mask:0xf
	v_fmac_f32_dpp v15, v19, v27 quad_perm:[1,0,3,2] row_mask:0xf bank_mask:0xf
	v_cvt_pk_f16_f32 v180, v16, v12
	v_cvt_pk_f16_f32 v184, v17, v13
	v_cvt_pk_f16_f32 v188, v18, v14
	v_cvt_pk_f16_f32 v192, v19, v15
	v_fma_f32 v16, v20, v12, v102
	v_fma_f32 v17, v21, v13, v118
	v_fma_f32 v18, v22, v14, v134
	v_fma_f32 v19, v23, v15, v150
	v_fmac_f32_dpp v16, v12, v24 quad_perm:[1,0,3,2] row_mask:0xf bank_mask:0xf
	v_fmac_f32_dpp v17, v13, v25 quad_perm:[1,0,3,2] row_mask:0xf bank_mask:0xf
	v_fmac_f32_dpp v18, v14, v26 quad_perm:[1,0,3,2] row_mask:0xf bank_mask:0xf
	v_fmac_f32_dpp v19, v15, v27 quad_perm:[1,0,3,2] row_mask:0xf bank_mask:0xf
	v_fma_f32 v12, v20, v16, v103
	v_fma_f32 v13, v21, v17, v119
	v_fma_f32 v14, v22, v18, v135
	v_fma_f32 v15, v23, v19, v151
	v_fmac_f32_dpp v12, v16, v24 quad_perm:[1,0,3,2] row_mask:0xf bank_mask:0xf
	v_fmac_f32_dpp v13, v17, v25 quad_perm:[1,0,3,2] row_mask:0xf bank_mask:0xf
	v_fmac_f32_dpp v14, v18, v26 quad_perm:[1,0,3,2] row_mask:0xf bank_mask:0xf
	v_fmac_f32_dpp v15, v19, v27 quad_perm:[1,0,3,2] row_mask:0xf bank_mask:0xf
	v_cvt_pk_f16_f32 v181, v16, v12
	v_cvt_pk_f16_f32 v185, v17, v13
	v_cvt_pk_f16_f32 v189, v18, v14
	v_cvt_pk_f16_f32 v193, v19, v15
	ds_write_b128 v84, v[178:181] offset:0
	ds_write_b128 v84, v[182:185] offset:512
	ds_write_b128 v84, v[186:189] offset:1024
	ds_write_b128 v84, v[190:193] offset:1536
	v_fma_f32 v16, v20, v12, v104
	v_fma_f32 v17, v21, v13, v120
	v_fma_f32 v18, v22, v14, v136
	v_fma_f32 v19, v23, v15, v152
	v_fmac_f32_dpp v16, v12, v24 quad_perm:[1,0,3,2] row_mask:0xf bank_mask:0xf
	v_fmac_f32_dpp v17, v13, v25 quad_perm:[1,0,3,2] row_mask:0xf bank_mask:0xf
	v_fmac_f32_dpp v18, v14, v26 quad_perm:[1,0,3,2] row_mask:0xf bank_mask:0xf
	v_fmac_f32_dpp v19, v15, v27 quad_perm:[1,0,3,2] row_mask:0xf bank_mask:0xf
	v_fma_f32 v12, v20, v16, v105
	v_fma_f32 v13, v21, v17, v121
	v_fma_f32 v14, v22, v18, v137
	v_fma_f32 v15, v23, v19, v153
	v_fmac_f32_dpp v12, v16, v24 quad_perm:[1,0,3,2] row_mask:0xf bank_mask:0xf
	v_fmac_f32_dpp v13, v17, v25 quad_perm:[1,0,3,2] row_mask:0xf bank_mask:0xf
	v_fmac_f32_dpp v14, v18, v26 quad_perm:[1,0,3,2] row_mask:0xf bank_mask:0xf
	v_fmac_f32_dpp v15, v19, v27 quad_perm:[1,0,3,2] row_mask:0xf bank_mask:0xf
	v_cvt_pk_f16_f32 v178, v16, v12
	v_cvt_pk_f16_f32 v182, v17, v13
	v_cvt_pk_f16_f32 v186, v18, v14
	v_cvt_pk_f16_f32 v190, v19, v15
	v_fma_f32 v16, v20, v12, v106
	v_fma_f32 v17, v21, v13, v122
	v_fma_f32 v18, v22, v14, v138
	v_fma_f32 v19, v23, v15, v154
	v_fmac_f32_dpp v16, v12, v24 quad_perm:[1,0,3,2] row_mask:0xf bank_mask:0xf
	v_fmac_f32_dpp v17, v13, v25 quad_perm:[1,0,3,2] row_mask:0xf bank_mask:0xf
	v_fmac_f32_dpp v18, v14, v26 quad_perm:[1,0,3,2] row_mask:0xf bank_mask:0xf
	v_fmac_f32_dpp v19, v15, v27 quad_perm:[1,0,3,2] row_mask:0xf bank_mask:0xf
	v_fma_f32 v12, v20, v16, v107
	v_fma_f32 v13, v21, v17, v123
	v_fma_f32 v14, v22, v18, v139
	v_fma_f32 v15, v23, v19, v155
	v_fmac_f32_dpp v12, v16, v24 quad_perm:[1,0,3,2] row_mask:0xf bank_mask:0xf
	v_fmac_f32_dpp v13, v17, v25 quad_perm:[1,0,3,2] row_mask:0xf bank_mask:0xf
	v_fmac_f32_dpp v14, v18, v26 quad_perm:[1,0,3,2] row_mask:0xf bank_mask:0xf
	v_fmac_f32_dpp v15, v19, v27 quad_perm:[1,0,3,2] row_mask:0xf bank_mask:0xf
	v_cvt_pk_f16_f32 v179, v16, v12
	v_cvt_pk_f16_f32 v183, v17, v13
	v_cvt_pk_f16_f32 v187, v18, v14
	v_cvt_pk_f16_f32 v191, v19, v15
	v_fma_f32 v16, v20, v12, v108
	v_fma_f32 v17, v21, v13, v124
	v_fma_f32 v18, v22, v14, v140
	v_fma_f32 v19, v23, v15, v156
	v_fmac_f32_dpp v16, v12, v24 quad_perm:[1,0,3,2] row_mask:0xf bank_mask:0xf
	v_fmac_f32_dpp v17, v13, v25 quad_perm:[1,0,3,2] row_mask:0xf bank_mask:0xf
	v_fmac_f32_dpp v18, v14, v26 quad_perm:[1,0,3,2] row_mask:0xf bank_mask:0xf
	v_fmac_f32_dpp v19, v15, v27 quad_perm:[1,0,3,2] row_mask:0xf bank_mask:0xf
	v_fma_f32 v12, v20, v16, v109
	v_fma_f32 v13, v21, v17, v125
	v_fma_f32 v14, v22, v18, v141
	v_fma_f32 v15, v23, v19, v157
	v_fmac_f32_dpp v12, v16, v24 quad_perm:[1,0,3,2] row_mask:0xf bank_mask:0xf
	v_fmac_f32_dpp v13, v17, v25 quad_perm:[1,0,3,2] row_mask:0xf bank_mask:0xf
	v_fmac_f32_dpp v14, v18, v26 quad_perm:[1,0,3,2] row_mask:0xf bank_mask:0xf
	v_fmac_f32_dpp v15, v19, v27 quad_perm:[1,0,3,2] row_mask:0xf bank_mask:0xf
	v_cvt_pk_f16_f32 v180, v16, v12
	v_cvt_pk_f16_f32 v184, v17, v13
	v_cvt_pk_f16_f32 v188, v18, v14
	v_cvt_pk_f16_f32 v192, v19, v15
	v_fma_f32 v16, v20, v12, v110
	v_fma_f32 v17, v21, v13, v126
	v_fma_f32 v18, v22, v14, v142
	v_fma_f32 v19, v23, v15, v158
	v_fmac_f32_dpp v16, v12, v24 quad_perm:[1,0,3,2] row_mask:0xf bank_mask:0xf
	v_fmac_f32_dpp v17, v13, v25 quad_perm:[1,0,3,2] row_mask:0xf bank_mask:0xf
	v_fmac_f32_dpp v18, v14, v26 quad_perm:[1,0,3,2] row_mask:0xf bank_mask:0xf
	v_fmac_f32_dpp v19, v15, v27 quad_perm:[1,0,3,2] row_mask:0xf bank_mask:0xf
	v_fma_f32 v12, v20, v16, v111
	v_fma_f32 v13, v21, v17, v127
	v_fma_f32 v14, v22, v18, v143
	v_fma_f32 v15, v23, v19, v159
	v_fmac_f32_dpp v12, v16, v24 quad_perm:[1,0,3,2] row_mask:0xf bank_mask:0xf
	v_fmac_f32_dpp v13, v17, v25 quad_perm:[1,0,3,2] row_mask:0xf bank_mask:0xf
	v_fmac_f32_dpp v14, v18, v26 quad_perm:[1,0,3,2] row_mask:0xf bank_mask:0xf
	v_fmac_f32_dpp v15, v19, v27 quad_perm:[1,0,3,2] row_mask:0xf bank_mask:0xf
	v_cvt_pk_f16_f32 v181, v16, v12
	v_cvt_pk_f16_f32 v185, v17, v13
	v_cvt_pk_f16_f32 v189, v18, v14
	v_cvt_pk_f16_f32 v193, v19, v15
	ds_write_b128 v84, v[178:181] offset:4160
	ds_write_b128 v84, v[182:185] offset:4672
	ds_write_b128 v84, v[186:189] offset:5184
	ds_write_b128 v84, v[190:193] offset:5696
	v_mfma_f32_32x32x16_f16 v[96:111], v[56:59], v[36:39], 0
	v_mfma_f32_32x32x16_f16 v[112:127], v[56:59], v[40:43], 0
	v_mfma_f32_32x32x16_f16 v[128:143], v[56:59], v[44:47], 0
	v_mfma_f32_32x32x16_f16 v[144:159], v[56:59], v[48:51], 0
	v_add_u32_e32 v93, s76, v87
	ds_read_b64_tr_b16 v[194:195], v85 offset:0
	ds_read_b64_tr_b16 v[196:197], v85 offset:64
	ds_read_b64_tr_b16 v[198:199], v85 offset:512
	ds_read_b64_tr_b16 v[200:201], v85 offset:576
	ds_read_b64_tr_b16 v[206:207], v85 offset:1024
	ds_read_b64_tr_b16 v[208:209], v85 offset:1088
	ds_read_b64_tr_b16 v[210:211], v85 offset:1536
	ds_read_b64_tr_b16 v[212:213], v85 offset:1600
	s_nop 3
	v_fma_f32 v16, v20, v12, v96
	v_fma_f32 v17, v21, v13, v112
	v_fma_f32 v18, v22, v14, v128
	v_fma_f32 v19, v23, v15, v144
	v_fmac_f32_dpp v16, v12, v24 quad_perm:[1,0,3,2] row_mask:0xf bank_mask:0xf
	v_fmac_f32_dpp v17, v13, v25 quad_perm:[1,0,3,2] row_mask:0xf bank_mask:0xf
	v_fmac_f32_dpp v18, v14, v26 quad_perm:[1,0,3,2] row_mask:0xf bank_mask:0xf
	v_fmac_f32_dpp v19, v15, v27 quad_perm:[1,0,3,2] row_mask:0xf bank_mask:0xf
	v_fma_f32 v12, v20, v16, v97
	v_fma_f32 v13, v21, v17, v113
	v_fma_f32 v14, v22, v18, v129
	v_fma_f32 v15, v23, v19, v145
	v_fmac_f32_dpp v12, v16, v24 quad_perm:[1,0,3,2] row_mask:0xf bank_mask:0xf
	v_fmac_f32_dpp v13, v17, v25 quad_perm:[1,0,3,2] row_mask:0xf bank_mask:0xf
	v_fmac_f32_dpp v14, v18, v26 quad_perm:[1,0,3,2] row_mask:0xf bank_mask:0xf
	v_fmac_f32_dpp v15, v19, v27 quad_perm:[1,0,3,2] row_mask:0xf bank_mask:0xf
	v_cvt_pk_f16_f32 v178, v16, v12
	v_cvt_pk_f16_f32 v182, v17, v13
	v_cvt_pk_f16_f32 v186, v18, v14
	v_cvt_pk_f16_f32 v190, v19, v15
	s_waitcnt lgkmcnt(6)
	v_mfma_f32_16x16x32_f16 v[32:35], v[160:163], v[194:197], 0
	s_waitcnt lgkmcnt(4)
	v_mfma_f32_16x16x32_f16 v[32:35], v[164:167], v[198:201], v[32:35]
	s_waitcnt lgkmcnt(2)
	v_mfma_f32_16x16x32_f16 v[32:35], v[168:171], v[206:209], v[32:35]
	s_waitcnt lgkmcnt(0)
	v_mfma_f32_16x16x32_f16 v[32:35], v[172:175], v[210:213], v[32:35]
	v_fma_f32 v16, v20, v12, v98
	v_fma_f32 v17, v21, v13, v114
	v_fma_f32 v18, v22, v14, v130
	v_fma_f32 v19, v23, v15, v146
	v_fmac_f32_dpp v16, v12, v24 quad_perm:[1,0,3,2] row_mask:0xf bank_mask:0xf
	v_fmac_f32_dpp v17, v13, v25 quad_perm:[1,0,3,2] row_mask:0xf bank_mask:0xf
	v_fmac_f32_dpp v18, v14, v26 quad_perm:[1,0,3,2] row_mask:0xf bank_mask:0xf
	v_fmac_f32_dpp v19, v15, v27 quad_perm:[1,0,3,2] row_mask:0xf bank_mask:0xf
	v_fma_f32 v12, v20, v16, v99
	v_fma_f32 v13, v21, v17, v115
	v_fma_f32 v14, v22, v18, v131
	v_fma_f32 v15, v23, v19, v147
	v_fmac_f32_dpp v12, v16, v24 quad_perm:[1,0,3,2] row_mask:0xf bank_mask:0xf
	v_fmac_f32_dpp v13, v17, v25 quad_perm:[1,0,3,2] row_mask:0xf bank_mask:0xf
	v_fmac_f32_dpp v14, v18, v26 quad_perm:[1,0,3,2] row_mask:0xf bank_mask:0xf
	v_fmac_f32_dpp v15, v19, v27 quad_perm:[1,0,3,2] row_mask:0xf bank_mask:0xf
	v_cvt_pk_f16_f32 v179, v16, v12
	v_cvt_pk_f16_f32 v183, v17, v13
	v_cvt_pk_f16_f32 v187, v18, v14
	v_cvt_pk_f16_f32 v191, v19, v15
	ds_write_b128 v93, v[32:35] offset:0
	ds_read_b64_tr_b16 v[194:195], v85 offset:2048
	ds_read_b64_tr_b16 v[196:197], v85 offset:2112
	ds_read_b64_tr_b16 v[198:199], v85 offset:2560
	ds_read_b64_tr_b16 v[200:201], v85 offset:2624
	ds_read_b64_tr_b16 v[206:207], v85 offset:3072
	ds_read_b64_tr_b16 v[208:209], v85 offset:3136
	ds_read_b64_tr_b16 v[210:211], v85 offset:3584
	ds_read_b64_tr_b16 v[212:213], v85 offset:3648
	v_fma_f32 v16, v20, v12, v100
	v_fma_f32 v17, v21, v13, v116
	v_fma_f32 v18, v22, v14, v132
	v_fma_f32 v19, v23, v15, v148
	v_fmac_f32_dpp v16, v12, v24 quad_perm:[1,0,3,2] row_mask:0xf bank_mask:0xf
	v_fmac_f32_dpp v17, v13, v25 quad_perm:[1,0,3,2] row_mask:0xf bank_mask:0xf
	v_fmac_f32_dpp v18, v14, v26 quad_perm:[1,0,3,2] row_mask:0xf bank_mask:0xf
	v_fmac_f32_dpp v19, v15, v27 quad_perm:[1,0,3,2] row_mask:0xf bank_mask:0xf
	v_fma_f32 v12, v20, v16, v101
	v_fma_f32 v13, v21, v17, v117
	v_fma_f32 v14, v22, v18, v133
	v_fma_f32 v15, v23, v19, v149
	v_fmac_f32_dpp v12, v16, v24 quad_perm:[1,0,3,2] row_mask:0xf bank_mask:0xf
	v_fmac_f32_dpp v13, v17, v25 quad_perm:[1,0,3,2] row_mask:0xf bank_mask:0xf
	v_fmac_f32_dpp v14, v18, v26 quad_perm:[1,0,3,2] row_mask:0xf bank_mask:0xf
	v_fmac_f32_dpp v15, v19, v27 quad_perm:[1,0,3,2] row_mask:0xf bank_mask:0xf
	v_cvt_pk_f16_f32 v180, v16, v12
	v_cvt_pk_f16_f32 v184, v17, v13
	v_cvt_pk_f16_f32 v188, v18, v14
	v_cvt_pk_f16_f32 v192, v19, v15
	s_waitcnt lgkmcnt(6)
	v_mfma_f32_16x16x32_f16 v[32:35], v[160:163], v[194:197], 0
	s_waitcnt lgkmcnt(4)
	v_mfma_f32_16x16x32_f16 v[32:35], v[164:167], v[198:201], v[32:35]
	s_waitcnt lgkmcnt(2)
	v_mfma_f32_16x16x32_f16 v[32:35], v[168:171], v[206:209], v[32:35]
	s_waitcnt lgkmcnt(0)
	v_mfma_f32_16x16x32_f16 v[32:35], v[172:175], v[210:213], v[32:35]
	v_fma_f32 v16, v20, v12, v102
	v_fma_f32 v17, v21, v13, v118
	v_fma_f32 v18, v22, v14, v134
	v_fma_f32 v19, v23, v15, v150
	v_fmac_f32_dpp v16, v12, v24 quad_perm:[1,0,3,2] row_mask:0xf bank_mask:0xf
	v_fmac_f32_dpp v17, v13, v25 quad_perm:[1,0,3,2] row_mask:0xf bank_mask:0xf
	v_fmac_f32_dpp v18, v14, v26 quad_perm:[1,0,3,2] row_mask:0xf bank_mask:0xf
	v_fmac_f32_dpp v19, v15, v27 quad_perm:[1,0,3,2] row_mask:0xf bank_mask:0xf
	v_fma_f32 v12, v20, v16, v103
	v_fma_f32 v13, v21, v17, v119
	v_fma_f32 v14, v22, v18, v135
	v_fma_f32 v15, v23, v19, v151
	v_fmac_f32_dpp v12, v16, v24 quad_perm:[1,0,3,2] row_mask:0xf bank_mask:0xf
	v_fmac_f32_dpp v13, v17, v25 quad_perm:[1,0,3,2] row_mask:0xf bank_mask:0xf
	v_fmac_f32_dpp v14, v18, v26 quad_perm:[1,0,3,2] row_mask:0xf bank_mask:0xf
	v_fmac_f32_dpp v15, v19, v27 quad_perm:[1,0,3,2] row_mask:0xf bank_mask:0xf
	v_cvt_pk_f16_f32 v181, v16, v12
	v_cvt_pk_f16_f32 v185, v17, v13
	v_cvt_pk_f16_f32 v189, v18, v14
	v_cvt_pk_f16_f32 v193, v19, v15
	ds_write_b128 v84, v[178:181] offset:0
	ds_write_b128 v84, v[182:185] offset:512
	ds_write_b128 v84, v[186:189] offset:1024
	ds_write_b128 v84, v[190:193] offset:1536
	v_fma_f32 v16, v20, v12, v104
	v_fma_f32 v17, v21, v13, v120
	v_fma_f32 v18, v22, v14, v136
	v_fma_f32 v19, v23, v15, v152
	v_fmac_f32_dpp v16, v12, v24 quad_perm:[1,0,3,2] row_mask:0xf bank_mask:0xf
	v_fmac_f32_dpp v17, v13, v25 quad_perm:[1,0,3,2] row_mask:0xf bank_mask:0xf
	v_fmac_f32_dpp v18, v14, v26 quad_perm:[1,0,3,2] row_mask:0xf bank_mask:0xf
	v_fmac_f32_dpp v19, v15, v27 quad_perm:[1,0,3,2] row_mask:0xf bank_mask:0xf
	ds_write_b128 v93, v[32:35] offset:4096
	v_fma_f32 v12, v20, v16, v105
	v_fma_f32 v13, v21, v17, v121
	v_fma_f32 v14, v22, v18, v137
	v_fma_f32 v15, v23, v19, v153
	v_fmac_f32_dpp v12, v16, v24 quad_perm:[1,0,3,2] row_mask:0xf bank_mask:0xf
	v_fmac_f32_dpp v13, v17, v25 quad_perm:[1,0,3,2] row_mask:0xf bank_mask:0xf
	v_fmac_f32_dpp v14, v18, v26 quad_perm:[1,0,3,2] row_mask:0xf bank_mask:0xf
	v_fmac_f32_dpp v15, v19, v27 quad_perm:[1,0,3,2] row_mask:0xf bank_mask:0xf
	v_cvt_pk_f16_f32 v178, v16, v12
	v_cvt_pk_f16_f32 v182, v17, v13
	v_cvt_pk_f16_f32 v186, v18, v14
	v_cvt_pk_f16_f32 v190, v19, v15
	v_fma_f32 v16, v20, v12, v106
	v_fma_f32 v17, v21, v13, v122
	v_fma_f32 v18, v22, v14, v138
	v_fma_f32 v19, v23, v15, v154
	v_fmac_f32_dpp v16, v12, v24 quad_perm:[1,0,3,2] row_mask:0xf bank_mask:0xf
	v_fmac_f32_dpp v17, v13, v25 quad_perm:[1,0,3,2] row_mask:0xf bank_mask:0xf
	v_fmac_f32_dpp v18, v14, v26 quad_perm:[1,0,3,2] row_mask:0xf bank_mask:0xf
	v_fmac_f32_dpp v19, v15, v27 quad_perm:[1,0,3,2] row_mask:0xf bank_mask:0xf
	v_fma_f32 v12, v20, v16, v107
	v_fma_f32 v13, v21, v17, v123
	v_fma_f32 v14, v22, v18, v139
	v_fma_f32 v15, v23, v19, v155
	v_fmac_f32_dpp v12, v16, v24 quad_perm:[1,0,3,2] row_mask:0xf bank_mask:0xf
	v_fmac_f32_dpp v13, v17, v25 quad_perm:[1,0,3,2] row_mask:0xf bank_mask:0xf
	v_fmac_f32_dpp v14, v18, v26 quad_perm:[1,0,3,2] row_mask:0xf bank_mask:0xf
	v_fmac_f32_dpp v15, v19, v27 quad_perm:[1,0,3,2] row_mask:0xf bank_mask:0xf
	v_cvt_pk_f16_f32 v179, v16, v12
	v_cvt_pk_f16_f32 v183, v17, v13
	v_cvt_pk_f16_f32 v187, v18, v14
	v_cvt_pk_f16_f32 v191, v19, v15
	v_fma_f32 v16, v20, v12, v108
	v_fma_f32 v17, v21, v13, v124
	v_fma_f32 v18, v22, v14, v140
	v_fma_f32 v19, v23, v15, v156
	v_fmac_f32_dpp v16, v12, v24 quad_perm:[1,0,3,2] row_mask:0xf bank_mask:0xf
	v_fmac_f32_dpp v17, v13, v25 quad_perm:[1,0,3,2] row_mask:0xf bank_mask:0xf
	v_fmac_f32_dpp v18, v14, v26 quad_perm:[1,0,3,2] row_mask:0xf bank_mask:0xf
	v_fmac_f32_dpp v19, v15, v27 quad_perm:[1,0,3,2] row_mask:0xf bank_mask:0xf
	v_fma_f32 v12, v20, v16, v109
	v_fma_f32 v13, v21, v17, v125
	v_fma_f32 v14, v22, v18, v141
	v_fma_f32 v15, v23, v19, v157
	v_fmac_f32_dpp v12, v16, v24 quad_perm:[1,0,3,2] row_mask:0xf bank_mask:0xf
	v_fmac_f32_dpp v13, v17, v25 quad_perm:[1,0,3,2] row_mask:0xf bank_mask:0xf
	v_fmac_f32_dpp v14, v18, v26 quad_perm:[1,0,3,2] row_mask:0xf bank_mask:0xf
	v_fmac_f32_dpp v15, v19, v27 quad_perm:[1,0,3,2] row_mask:0xf bank_mask:0xf
	v_cvt_pk_f16_f32 v180, v16, v12
	v_cvt_pk_f16_f32 v184, v17, v13
	v_cvt_pk_f16_f32 v188, v18, v14
	v_cvt_pk_f16_f32 v192, v19, v15
	v_fma_f32 v16, v20, v12, v110
	v_fma_f32 v17, v21, v13, v126
	v_fma_f32 v18, v22, v14, v142
	v_fma_f32 v19, v23, v15, v158
	v_fmac_f32_dpp v16, v12, v24 quad_perm:[1,0,3,2] row_mask:0xf bank_mask:0xf
	v_fmac_f32_dpp v17, v13, v25 quad_perm:[1,0,3,2] row_mask:0xf bank_mask:0xf
	v_fmac_f32_dpp v18, v14, v26 quad_perm:[1,0,3,2] row_mask:0xf bank_mask:0xf
	v_fmac_f32_dpp v19, v15, v27 quad_perm:[1,0,3,2] row_mask:0xf bank_mask:0xf
	v_fma_f32 v12, v20, v16, v111
	v_fma_f32 v13, v21, v17, v127
	v_fma_f32 v14, v22, v18, v143
	v_fma_f32 v15, v23, v19, v159
	v_fmac_f32_dpp v12, v16, v24 quad_perm:[1,0,3,2] row_mask:0xf bank_mask:0xf
	v_fmac_f32_dpp v13, v17, v25 quad_perm:[1,0,3,2] row_mask:0xf bank_mask:0xf
	v_fmac_f32_dpp v14, v18, v26 quad_perm:[1,0,3,2] row_mask:0xf bank_mask:0xf
	v_fmac_f32_dpp v15, v19, v27 quad_perm:[1,0,3,2] row_mask:0xf bank_mask:0xf
	v_cvt_pk_f16_f32 v181, v16, v12
	v_cvt_pk_f16_f32 v185, v17, v13
	v_cvt_pk_f16_f32 v189, v18, v14
	v_cvt_pk_f16_f32 v193, v19, v15
	ds_write_b128 v84, v[178:181] offset:4160
	ds_write_b128 v84, v[182:185] offset:4672
	ds_write_b128 v84, v[186:189] offset:5184
	ds_write_b128 v84, v[190:193] offset:5696
	v_mfma_f32_32x32x16_f16 v[96:111], v[60:63], v[36:39], 0
	v_mfma_f32_32x32x16_f16 v[112:127], v[60:63], v[40:43], 0
	v_mfma_f32_32x32x16_f16 v[128:143], v[60:63], v[44:47], 0
	v_mfma_f32_32x32x16_f16 v[144:159], v[60:63], v[48:51], 0
	v_add_u32_e32 v93, s77, v87
	ds_read_b64_tr_b16 v[194:195], v85 offset:0
	ds_read_b64_tr_b16 v[196:197], v85 offset:64
	ds_read_b64_tr_b16 v[198:199], v85 offset:512
	ds_read_b64_tr_b16 v[200:201], v85 offset:576
	ds_read_b64_tr_b16 v[206:207], v85 offset:1024
	ds_read_b64_tr_b16 v[208:209], v85 offset:1088
	ds_read_b64_tr_b16 v[210:211], v85 offset:1536
	ds_read_b64_tr_b16 v[212:213], v85 offset:1600
	s_nop 3
	v_fma_f32 v16, v20, v12, v96
	v_fma_f32 v17, v21, v13, v112
	v_fma_f32 v18, v22, v14, v128
	v_fma_f32 v19, v23, v15, v144
	v_fmac_f32_dpp v16, v12, v24 quad_perm:[1,0,3,2] row_mask:0xf bank_mask:0xf
	v_fmac_f32_dpp v17, v13, v25 quad_perm:[1,0,3,2] row_mask:0xf bank_mask:0xf
	v_fmac_f32_dpp v18, v14, v26 quad_perm:[1,0,3,2] row_mask:0xf bank_mask:0xf
	v_fmac_f32_dpp v19, v15, v27 quad_perm:[1,0,3,2] row_mask:0xf bank_mask:0xf
	v_fma_f32 v12, v20, v16, v97
	v_fma_f32 v13, v21, v17, v113
	v_fma_f32 v14, v22, v18, v129
	v_fma_f32 v15, v23, v19, v145
	v_fmac_f32_dpp v12, v16, v24 quad_perm:[1,0,3,2] row_mask:0xf bank_mask:0xf
	v_fmac_f32_dpp v13, v17, v25 quad_perm:[1,0,3,2] row_mask:0xf bank_mask:0xf
	v_fmac_f32_dpp v14, v18, v26 quad_perm:[1,0,3,2] row_mask:0xf bank_mask:0xf
	v_fmac_f32_dpp v15, v19, v27 quad_perm:[1,0,3,2] row_mask:0xf bank_mask:0xf
	v_cvt_pk_f16_f32 v178, v16, v12
	v_cvt_pk_f16_f32 v182, v17, v13
	v_cvt_pk_f16_f32 v186, v18, v14
	v_cvt_pk_f16_f32 v190, v19, v15
	s_waitcnt lgkmcnt(6)
	v_mfma_f32_16x16x32_f16 v[32:35], v[160:163], v[194:197], 0
	s_waitcnt lgkmcnt(4)
	v_mfma_f32_16x16x32_f16 v[32:35], v[164:167], v[198:201], v[32:35]
	s_waitcnt lgkmcnt(2)
	v_mfma_f32_16x16x32_f16 v[32:35], v[168:171], v[206:209], v[32:35]
	s_waitcnt lgkmcnt(0)
	v_mfma_f32_16x16x32_f16 v[32:35], v[172:175], v[210:213], v[32:35]
	v_fma_f32 v16, v20, v12, v98
	v_fma_f32 v17, v21, v13, v114
	v_fma_f32 v18, v22, v14, v130
	v_fma_f32 v19, v23, v15, v146
	v_fmac_f32_dpp v16, v12, v24 quad_perm:[1,0,3,2] row_mask:0xf bank_mask:0xf
	v_fmac_f32_dpp v17, v13, v25 quad_perm:[1,0,3,2] row_mask:0xf bank_mask:0xf
	v_fmac_f32_dpp v18, v14, v26 quad_perm:[1,0,3,2] row_mask:0xf bank_mask:0xf
	v_fmac_f32_dpp v19, v15, v27 quad_perm:[1,0,3,2] row_mask:0xf bank_mask:0xf
	v_fma_f32 v12, v20, v16, v99
	v_fma_f32 v13, v21, v17, v115
	v_fma_f32 v14, v22, v18, v131
	v_fma_f32 v15, v23, v19, v147
	v_fmac_f32_dpp v12, v16, v24 quad_perm:[1,0,3,2] row_mask:0xf bank_mask:0xf
	v_fmac_f32_dpp v13, v17, v25 quad_perm:[1,0,3,2] row_mask:0xf bank_mask:0xf
	v_fmac_f32_dpp v14, v18, v26 quad_perm:[1,0,3,2] row_mask:0xf bank_mask:0xf
	v_fmac_f32_dpp v15, v19, v27 quad_perm:[1,0,3,2] row_mask:0xf bank_mask:0xf
	v_cvt_pk_f16_f32 v179, v16, v12
	v_cvt_pk_f16_f32 v183, v17, v13
	v_cvt_pk_f16_f32 v187, v18, v14
	v_cvt_pk_f16_f32 v191, v19, v15
	ds_write_b128 v93, v[32:35] offset:0
	ds_read_b64_tr_b16 v[194:195], v85 offset:2048
	ds_read_b64_tr_b16 v[196:197], v85 offset:2112
	ds_read_b64_tr_b16 v[198:199], v85 offset:2560
	ds_read_b64_tr_b16 v[200:201], v85 offset:2624
	ds_read_b64_tr_b16 v[206:207], v85 offset:3072
	ds_read_b64_tr_b16 v[208:209], v85 offset:3136
	ds_read_b64_tr_b16 v[210:211], v85 offset:3584
	ds_read_b64_tr_b16 v[212:213], v85 offset:3648
	v_fma_f32 v16, v20, v12, v100
	v_fma_f32 v17, v21, v13, v116
	v_fma_f32 v18, v22, v14, v132
	v_fma_f32 v19, v23, v15, v148
	v_fmac_f32_dpp v16, v12, v24 quad_perm:[1,0,3,2] row_mask:0xf bank_mask:0xf
	v_fmac_f32_dpp v17, v13, v25 quad_perm:[1,0,3,2] row_mask:0xf bank_mask:0xf
	v_fmac_f32_dpp v18, v14, v26 quad_perm:[1,0,3,2] row_mask:0xf bank_mask:0xf
	v_fmac_f32_dpp v19, v15, v27 quad_perm:[1,0,3,2] row_mask:0xf bank_mask:0xf
	v_fma_f32 v12, v20, v16, v101
	v_fma_f32 v13, v21, v17, v117
	v_fma_f32 v14, v22, v18, v133
	v_fma_f32 v15, v23, v19, v149
	v_fmac_f32_dpp v12, v16, v24 quad_perm:[1,0,3,2] row_mask:0xf bank_mask:0xf
	v_fmac_f32_dpp v13, v17, v25 quad_perm:[1,0,3,2] row_mask:0xf bank_mask:0xf
	v_fmac_f32_dpp v14, v18, v26 quad_perm:[1,0,3,2] row_mask:0xf bank_mask:0xf
	v_fmac_f32_dpp v15, v19, v27 quad_perm:[1,0,3,2] row_mask:0xf bank_mask:0xf
	v_cvt_pk_f16_f32 v180, v16, v12
	v_cvt_pk_f16_f32 v184, v17, v13
	v_cvt_pk_f16_f32 v188, v18, v14
	v_cvt_pk_f16_f32 v192, v19, v15
	s_waitcnt lgkmcnt(6)
	v_mfma_f32_16x16x32_f16 v[32:35], v[160:163], v[194:197], 0
	s_waitcnt lgkmcnt(4)
	v_mfma_f32_16x16x32_f16 v[32:35], v[164:167], v[198:201], v[32:35]
	s_waitcnt lgkmcnt(2)
	v_mfma_f32_16x16x32_f16 v[32:35], v[168:171], v[206:209], v[32:35]
	s_waitcnt lgkmcnt(0)
	v_mfma_f32_16x16x32_f16 v[32:35], v[172:175], v[210:213], v[32:35]
	v_fma_f32 v16, v20, v12, v102
	v_fma_f32 v17, v21, v13, v118
	v_fma_f32 v18, v22, v14, v134
	v_fma_f32 v19, v23, v15, v150
	v_fmac_f32_dpp v16, v12, v24 quad_perm:[1,0,3,2] row_mask:0xf bank_mask:0xf
	v_fmac_f32_dpp v17, v13, v25 quad_perm:[1,0,3,2] row_mask:0xf bank_mask:0xf
	v_fmac_f32_dpp v18, v14, v26 quad_perm:[1,0,3,2] row_mask:0xf bank_mask:0xf
	v_fmac_f32_dpp v19, v15, v27 quad_perm:[1,0,3,2] row_mask:0xf bank_mask:0xf
	v_fma_f32 v12, v20, v16, v103
	v_fma_f32 v13, v21, v17, v119
	v_fma_f32 v14, v22, v18, v135
	v_fma_f32 v15, v23, v19, v151
	v_fmac_f32_dpp v12, v16, v24 quad_perm:[1,0,3,2] row_mask:0xf bank_mask:0xf
	v_fmac_f32_dpp v13, v17, v25 quad_perm:[1,0,3,2] row_mask:0xf bank_mask:0xf
	v_fmac_f32_dpp v14, v18, v26 quad_perm:[1,0,3,2] row_mask:0xf bank_mask:0xf
	v_fmac_f32_dpp v15, v19, v27 quad_perm:[1,0,3,2] row_mask:0xf bank_mask:0xf
	v_cvt_pk_f16_f32 v181, v16, v12
	v_cvt_pk_f16_f32 v185, v17, v13
	v_cvt_pk_f16_f32 v189, v18, v14
	v_cvt_pk_f16_f32 v193, v19, v15
	ds_write_b128 v84, v[178:181] offset:0
	ds_write_b128 v84, v[182:185] offset:512
	ds_write_b128 v84, v[186:189] offset:1024
	ds_write_b128 v84, v[190:193] offset:1536
	v_fma_f32 v16, v20, v12, v104
	v_fma_f32 v17, v21, v13, v120
	v_fma_f32 v18, v22, v14, v136
	v_fma_f32 v19, v23, v15, v152
	v_fmac_f32_dpp v16, v12, v24 quad_perm:[1,0,3,2] row_mask:0xf bank_mask:0xf
	v_fmac_f32_dpp v17, v13, v25 quad_perm:[1,0,3,2] row_mask:0xf bank_mask:0xf
	v_fmac_f32_dpp v18, v14, v26 quad_perm:[1,0,3,2] row_mask:0xf bank_mask:0xf
	v_fmac_f32_dpp v19, v15, v27 quad_perm:[1,0,3,2] row_mask:0xf bank_mask:0xf
	ds_write_b128 v93, v[32:35] offset:4096
	v_fma_f32 v12, v20, v16, v105
	v_fma_f32 v13, v21, v17, v121
	v_fma_f32 v14, v22, v18, v137
	v_fma_f32 v15, v23, v19, v153
	v_fmac_f32_dpp v12, v16, v24 quad_perm:[1,0,3,2] row_mask:0xf bank_mask:0xf
	v_fmac_f32_dpp v13, v17, v25 quad_perm:[1,0,3,2] row_mask:0xf bank_mask:0xf
	v_fmac_f32_dpp v14, v18, v26 quad_perm:[1,0,3,2] row_mask:0xf bank_mask:0xf
	v_fmac_f32_dpp v15, v19, v27 quad_perm:[1,0,3,2] row_mask:0xf bank_mask:0xf
	v_cvt_pk_f16_f32 v178, v16, v12
	v_cvt_pk_f16_f32 v182, v17, v13
	v_cvt_pk_f16_f32 v186, v18, v14
	v_cvt_pk_f16_f32 v190, v19, v15
	v_fma_f32 v16, v20, v12, v106
	v_fma_f32 v17, v21, v13, v122
	v_fma_f32 v18, v22, v14, v138
	v_fma_f32 v19, v23, v15, v154
	v_fmac_f32_dpp v16, v12, v24 quad_perm:[1,0,3,2] row_mask:0xf bank_mask:0xf
	v_fmac_f32_dpp v17, v13, v25 quad_perm:[1,0,3,2] row_mask:0xf bank_mask:0xf
	v_fmac_f32_dpp v18, v14, v26 quad_perm:[1,0,3,2] row_mask:0xf bank_mask:0xf
	v_fmac_f32_dpp v19, v15, v27 quad_perm:[1,0,3,2] row_mask:0xf bank_mask:0xf
	v_fma_f32 v12, v20, v16, v107
	v_fma_f32 v13, v21, v17, v123
	v_fma_f32 v14, v22, v18, v139
	v_fma_f32 v15, v23, v19, v155
	v_fmac_f32_dpp v12, v16, v24 quad_perm:[1,0,3,2] row_mask:0xf bank_mask:0xf
	v_fmac_f32_dpp v13, v17, v25 quad_perm:[1,0,3,2] row_mask:0xf bank_mask:0xf
	v_fmac_f32_dpp v14, v18, v26 quad_perm:[1,0,3,2] row_mask:0xf bank_mask:0xf
	v_fmac_f32_dpp v15, v19, v27 quad_perm:[1,0,3,2] row_mask:0xf bank_mask:0xf
	v_cvt_pk_f16_f32 v179, v16, v12
	v_cvt_pk_f16_f32 v183, v17, v13
	v_cvt_pk_f16_f32 v187, v18, v14
	v_cvt_pk_f16_f32 v191, v19, v15
	v_fma_f32 v16, v20, v12, v108
	v_fma_f32 v17, v21, v13, v124
	v_fma_f32 v18, v22, v14, v140
	v_fma_f32 v19, v23, v15, v156
	v_fmac_f32_dpp v16, v12, v24 quad_perm:[1,0,3,2] row_mask:0xf bank_mask:0xf
	v_fmac_f32_dpp v17, v13, v25 quad_perm:[1,0,3,2] row_mask:0xf bank_mask:0xf
	v_fmac_f32_dpp v18, v14, v26 quad_perm:[1,0,3,2] row_mask:0xf bank_mask:0xf
	v_fmac_f32_dpp v19, v15, v27 quad_perm:[1,0,3,2] row_mask:0xf bank_mask:0xf
	v_fma_f32 v12, v20, v16, v109
	v_fma_f32 v13, v21, v17, v125
	v_fma_f32 v14, v22, v18, v141
	v_fma_f32 v15, v23, v19, v157
	v_fmac_f32_dpp v12, v16, v24 quad_perm:[1,0,3,2] row_mask:0xf bank_mask:0xf
	v_fmac_f32_dpp v13, v17, v25 quad_perm:[1,0,3,2] row_mask:0xf bank_mask:0xf
	v_fmac_f32_dpp v14, v18, v26 quad_perm:[1,0,3,2] row_mask:0xf bank_mask:0xf
	v_fmac_f32_dpp v15, v19, v27 quad_perm:[1,0,3,2] row_mask:0xf bank_mask:0xf
	v_cvt_pk_f16_f32 v180, v16, v12
	v_cvt_pk_f16_f32 v184, v17, v13
	v_cvt_pk_f16_f32 v188, v18, v14
	v_cvt_pk_f16_f32 v192, v19, v15
	v_fma_f32 v16, v20, v12, v110
	v_fma_f32 v17, v21, v13, v126
	v_fma_f32 v18, v22, v14, v142
	v_fma_f32 v19, v23, v15, v158
	v_fmac_f32_dpp v16, v12, v24 quad_perm:[1,0,3,2] row_mask:0xf bank_mask:0xf
	v_fmac_f32_dpp v17, v13, v25 quad_perm:[1,0,3,2] row_mask:0xf bank_mask:0xf
	v_fmac_f32_dpp v18, v14, v26 quad_perm:[1,0,3,2] row_mask:0xf bank_mask:0xf
	v_fmac_f32_dpp v19, v15, v27 quad_perm:[1,0,3,2] row_mask:0xf bank_mask:0xf
	v_fma_f32 v12, v20, v16, v111
	v_fma_f32 v13, v21, v17, v127
	v_fma_f32 v14, v22, v18, v143
	v_fma_f32 v15, v23, v19, v159
	v_fmac_f32_dpp v12, v16, v24 quad_perm:[1,0,3,2] row_mask:0xf bank_mask:0xf
	v_fmac_f32_dpp v13, v17, v25 quad_perm:[1,0,3,2] row_mask:0xf bank_mask:0xf
	v_fmac_f32_dpp v14, v18, v26 quad_perm:[1,0,3,2] row_mask:0xf bank_mask:0xf
	v_fmac_f32_dpp v15, v19, v27 quad_perm:[1,0,3,2] row_mask:0xf bank_mask:0xf
	v_cvt_pk_f16_f32 v181, v16, v12
	v_cvt_pk_f16_f32 v185, v17, v13
	v_cvt_pk_f16_f32 v189, v18, v14
	v_cvt_pk_f16_f32 v193, v19, v15
	ds_write_b128 v84, v[178:181] offset:4160
	ds_write_b128 v84, v[182:185] offset:4672
	ds_write_b128 v84, v[186:189] offset:5184
	ds_write_b128 v84, v[190:193] offset:5696
	v_mfma_f32_32x32x16_f16 v[96:111], v[64:67], v[36:39], 0
	v_mfma_f32_32x32x16_f16 v[112:127], v[64:67], v[40:43], 0
	v_mfma_f32_32x32x16_f16 v[128:143], v[64:67], v[44:47], 0
	v_mfma_f32_32x32x16_f16 v[144:159], v[64:67], v[48:51], 0
	v_add_u32_e32 v93, s78, v87
	ds_read_b64_tr_b16 v[194:195], v85 offset:0
	ds_read_b64_tr_b16 v[196:197], v85 offset:64
	ds_read_b64_tr_b16 v[198:199], v85 offset:512
	ds_read_b64_tr_b16 v[200:201], v85 offset:576
	ds_read_b64_tr_b16 v[206:207], v85 offset:1024
	ds_read_b64_tr_b16 v[208:209], v85 offset:1088
	ds_read_b64_tr_b16 v[210:211], v85 offset:1536
	ds_read_b64_tr_b16 v[212:213], v85 offset:1600
	s_nop 3
	v_fma_f32 v16, v20, v12, v96
	v_fma_f32 v17, v21, v13, v112
	v_fma_f32 v18, v22, v14, v128
	v_fma_f32 v19, v23, v15, v144
	v_fmac_f32_dpp v16, v12, v24 quad_perm:[1,0,3,2] row_mask:0xf bank_mask:0xf
	v_fmac_f32_dpp v17, v13, v25 quad_perm:[1,0,3,2] row_mask:0xf bank_mask:0xf
	v_fmac_f32_dpp v18, v14, v26 quad_perm:[1,0,3,2] row_mask:0xf bank_mask:0xf
	v_fmac_f32_dpp v19, v15, v27 quad_perm:[1,0,3,2] row_mask:0xf bank_mask:0xf
	v_fma_f32 v12, v20, v16, v97
	v_fma_f32 v13, v21, v17, v113
	v_fma_f32 v14, v22, v18, v129
	v_fma_f32 v15, v23, v19, v145
	v_fmac_f32_dpp v12, v16, v24 quad_perm:[1,0,3,2] row_mask:0xf bank_mask:0xf
	v_fmac_f32_dpp v13, v17, v25 quad_perm:[1,0,3,2] row_mask:0xf bank_mask:0xf
	v_fmac_f32_dpp v14, v18, v26 quad_perm:[1,0,3,2] row_mask:0xf bank_mask:0xf
	v_fmac_f32_dpp v15, v19, v27 quad_perm:[1,0,3,2] row_mask:0xf bank_mask:0xf
	v_cvt_pk_f16_f32 v178, v16, v12
	v_cvt_pk_f16_f32 v182, v17, v13
	v_cvt_pk_f16_f32 v186, v18, v14
	v_cvt_pk_f16_f32 v190, v19, v15
	s_waitcnt lgkmcnt(6)
	v_mfma_f32_16x16x32_f16 v[32:35], v[160:163], v[194:197], 0
	s_waitcnt lgkmcnt(4)
	v_mfma_f32_16x16x32_f16 v[32:35], v[164:167], v[198:201], v[32:35]
	s_waitcnt lgkmcnt(2)
	v_mfma_f32_16x16x32_f16 v[32:35], v[168:171], v[206:209], v[32:35]
	s_waitcnt lgkmcnt(0)
	v_mfma_f32_16x16x32_f16 v[32:35], v[172:175], v[210:213], v[32:35]
	v_fma_f32 v16, v20, v12, v98
	v_fma_f32 v17, v21, v13, v114
	v_fma_f32 v18, v22, v14, v130
	v_fma_f32 v19, v23, v15, v146
	v_fmac_f32_dpp v16, v12, v24 quad_perm:[1,0,3,2] row_mask:0xf bank_mask:0xf
	v_fmac_f32_dpp v17, v13, v25 quad_perm:[1,0,3,2] row_mask:0xf bank_mask:0xf
	v_fmac_f32_dpp v18, v14, v26 quad_perm:[1,0,3,2] row_mask:0xf bank_mask:0xf
	v_fmac_f32_dpp v19, v15, v27 quad_perm:[1,0,3,2] row_mask:0xf bank_mask:0xf
	v_fma_f32 v12, v20, v16, v99
	v_fma_f32 v13, v21, v17, v115
	v_fma_f32 v14, v22, v18, v131
	v_fma_f32 v15, v23, v19, v147
	v_fmac_f32_dpp v12, v16, v24 quad_perm:[1,0,3,2] row_mask:0xf bank_mask:0xf
	v_fmac_f32_dpp v13, v17, v25 quad_perm:[1,0,3,2] row_mask:0xf bank_mask:0xf
	v_fmac_f32_dpp v14, v18, v26 quad_perm:[1,0,3,2] row_mask:0xf bank_mask:0xf
	v_fmac_f32_dpp v15, v19, v27 quad_perm:[1,0,3,2] row_mask:0xf bank_mask:0xf
	v_cvt_pk_f16_f32 v179, v16, v12
	v_cvt_pk_f16_f32 v183, v17, v13
	v_cvt_pk_f16_f32 v187, v18, v14
	v_cvt_pk_f16_f32 v191, v19, v15
	ds_write_b128 v93, v[32:35] offset:0
	ds_read_b64_tr_b16 v[194:195], v85 offset:2048
	ds_read_b64_tr_b16 v[196:197], v85 offset:2112
	ds_read_b64_tr_b16 v[198:199], v85 offset:2560
	ds_read_b64_tr_b16 v[200:201], v85 offset:2624
	ds_read_b64_tr_b16 v[206:207], v85 offset:3072
	ds_read_b64_tr_b16 v[208:209], v85 offset:3136
	ds_read_b64_tr_b16 v[210:211], v85 offset:3584
	ds_read_b64_tr_b16 v[212:213], v85 offset:3648
	v_fma_f32 v16, v20, v12, v100
	v_fma_f32 v17, v21, v13, v116
	v_fma_f32 v18, v22, v14, v132
	v_fma_f32 v19, v23, v15, v148
	v_fmac_f32_dpp v16, v12, v24 quad_perm:[1,0,3,2] row_mask:0xf bank_mask:0xf
	v_fmac_f32_dpp v17, v13, v25 quad_perm:[1,0,3,2] row_mask:0xf bank_mask:0xf
	v_fmac_f32_dpp v18, v14, v26 quad_perm:[1,0,3,2] row_mask:0xf bank_mask:0xf
	v_fmac_f32_dpp v19, v15, v27 quad_perm:[1,0,3,2] row_mask:0xf bank_mask:0xf
	v_fma_f32 v12, v20, v16, v101
	v_fma_f32 v13, v21, v17, v117
	v_fma_f32 v14, v22, v18, v133
	v_fma_f32 v15, v23, v19, v149
	v_fmac_f32_dpp v12, v16, v24 quad_perm:[1,0,3,2] row_mask:0xf bank_mask:0xf
	v_fmac_f32_dpp v13, v17, v25 quad_perm:[1,0,3,2] row_mask:0xf bank_mask:0xf
	v_fmac_f32_dpp v14, v18, v26 quad_perm:[1,0,3,2] row_mask:0xf bank_mask:0xf
	v_fmac_f32_dpp v15, v19, v27 quad_perm:[1,0,3,2] row_mask:0xf bank_mask:0xf
	v_cvt_pk_f16_f32 v180, v16, v12
	v_cvt_pk_f16_f32 v184, v17, v13
	v_cvt_pk_f16_f32 v188, v18, v14
	v_cvt_pk_f16_f32 v192, v19, v15
	s_waitcnt lgkmcnt(6)
	v_mfma_f32_16x16x32_f16 v[32:35], v[160:163], v[194:197], 0
	s_waitcnt lgkmcnt(4)
	v_mfma_f32_16x16x32_f16 v[32:35], v[164:167], v[198:201], v[32:35]
	s_waitcnt lgkmcnt(2)
	v_mfma_f32_16x16x32_f16 v[32:35], v[168:171], v[206:209], v[32:35]
	s_waitcnt lgkmcnt(0)
	v_mfma_f32_16x16x32_f16 v[32:35], v[172:175], v[210:213], v[32:35]
	v_fma_f32 v16, v20, v12, v102
	v_fma_f32 v17, v21, v13, v118
	v_fma_f32 v18, v22, v14, v134
	v_fma_f32 v19, v23, v15, v150
	v_fmac_f32_dpp v16, v12, v24 quad_perm:[1,0,3,2] row_mask:0xf bank_mask:0xf
	v_fmac_f32_dpp v17, v13, v25 quad_perm:[1,0,3,2] row_mask:0xf bank_mask:0xf
	v_fmac_f32_dpp v18, v14, v26 quad_perm:[1,0,3,2] row_mask:0xf bank_mask:0xf
	v_fmac_f32_dpp v19, v15, v27 quad_perm:[1,0,3,2] row_mask:0xf bank_mask:0xf
	v_fma_f32 v12, v20, v16, v103
	v_fma_f32 v13, v21, v17, v119
	v_fma_f32 v14, v22, v18, v135
	v_fma_f32 v15, v23, v19, v151
	v_fmac_f32_dpp v12, v16, v24 quad_perm:[1,0,3,2] row_mask:0xf bank_mask:0xf
	v_fmac_f32_dpp v13, v17, v25 quad_perm:[1,0,3,2] row_mask:0xf bank_mask:0xf
	v_fmac_f32_dpp v14, v18, v26 quad_perm:[1,0,3,2] row_mask:0xf bank_mask:0xf
	v_fmac_f32_dpp v15, v19, v27 quad_perm:[1,0,3,2] row_mask:0xf bank_mask:0xf
	v_cvt_pk_f16_f32 v181, v16, v12
	v_cvt_pk_f16_f32 v185, v17, v13
	v_cvt_pk_f16_f32 v189, v18, v14
	v_cvt_pk_f16_f32 v193, v19, v15
	ds_write_b128 v84, v[178:181] offset:0
	ds_write_b128 v84, v[182:185] offset:512
	ds_write_b128 v84, v[186:189] offset:1024
	ds_write_b128 v84, v[190:193] offset:1536
	v_fma_f32 v16, v20, v12, v104
	v_fma_f32 v17, v21, v13, v120
	v_fma_f32 v18, v22, v14, v136
	v_fma_f32 v19, v23, v15, v152
	v_fmac_f32_dpp v16, v12, v24 quad_perm:[1,0,3,2] row_mask:0xf bank_mask:0xf
	v_fmac_f32_dpp v17, v13, v25 quad_perm:[1,0,3,2] row_mask:0xf bank_mask:0xf
	v_fmac_f32_dpp v18, v14, v26 quad_perm:[1,0,3,2] row_mask:0xf bank_mask:0xf
	v_fmac_f32_dpp v19, v15, v27 quad_perm:[1,0,3,2] row_mask:0xf bank_mask:0xf
	ds_write_b128 v93, v[32:35] offset:4096
	v_fma_f32 v12, v20, v16, v105
	v_fma_f32 v13, v21, v17, v121
	v_fma_f32 v14, v22, v18, v137
	v_fma_f32 v15, v23, v19, v153
	v_fmac_f32_dpp v12, v16, v24 quad_perm:[1,0,3,2] row_mask:0xf bank_mask:0xf
	v_fmac_f32_dpp v13, v17, v25 quad_perm:[1,0,3,2] row_mask:0xf bank_mask:0xf
	v_fmac_f32_dpp v14, v18, v26 quad_perm:[1,0,3,2] row_mask:0xf bank_mask:0xf
	v_fmac_f32_dpp v15, v19, v27 quad_perm:[1,0,3,2] row_mask:0xf bank_mask:0xf
	v_cvt_pk_f16_f32 v178, v16, v12
	v_cvt_pk_f16_f32 v182, v17, v13
	v_cvt_pk_f16_f32 v186, v18, v14
	v_cvt_pk_f16_f32 v190, v19, v15
	v_fma_f32 v16, v20, v12, v106
	v_fma_f32 v17, v21, v13, v122
	v_fma_f32 v18, v22, v14, v138
	v_fma_f32 v19, v23, v15, v154
	v_fmac_f32_dpp v16, v12, v24 quad_perm:[1,0,3,2] row_mask:0xf bank_mask:0xf
	v_fmac_f32_dpp v17, v13, v25 quad_perm:[1,0,3,2] row_mask:0xf bank_mask:0xf
	v_fmac_f32_dpp v18, v14, v26 quad_perm:[1,0,3,2] row_mask:0xf bank_mask:0xf
	v_fmac_f32_dpp v19, v15, v27 quad_perm:[1,0,3,2] row_mask:0xf bank_mask:0xf
	v_fma_f32 v12, v20, v16, v107
	v_fma_f32 v13, v21, v17, v123
	v_fma_f32 v14, v22, v18, v139
	v_fma_f32 v15, v23, v19, v155
	v_fmac_f32_dpp v12, v16, v24 quad_perm:[1,0,3,2] row_mask:0xf bank_mask:0xf
	v_fmac_f32_dpp v13, v17, v25 quad_perm:[1,0,3,2] row_mask:0xf bank_mask:0xf
	v_fmac_f32_dpp v14, v18, v26 quad_perm:[1,0,3,2] row_mask:0xf bank_mask:0xf
	v_fmac_f32_dpp v15, v19, v27 quad_perm:[1,0,3,2] row_mask:0xf bank_mask:0xf
	v_cvt_pk_f16_f32 v179, v16, v12
	v_cvt_pk_f16_f32 v183, v17, v13
	v_cvt_pk_f16_f32 v187, v18, v14
	v_cvt_pk_f16_f32 v191, v19, v15
	v_fma_f32 v16, v20, v12, v108
	v_fma_f32 v17, v21, v13, v124
	v_fma_f32 v18, v22, v14, v140
	v_fma_f32 v19, v23, v15, v156
	v_fmac_f32_dpp v16, v12, v24 quad_perm:[1,0,3,2] row_mask:0xf bank_mask:0xf
	v_fmac_f32_dpp v17, v13, v25 quad_perm:[1,0,3,2] row_mask:0xf bank_mask:0xf
	v_fmac_f32_dpp v18, v14, v26 quad_perm:[1,0,3,2] row_mask:0xf bank_mask:0xf
	v_fmac_f32_dpp v19, v15, v27 quad_perm:[1,0,3,2] row_mask:0xf bank_mask:0xf
	v_fma_f32 v12, v20, v16, v109
	v_fma_f32 v13, v21, v17, v125
	v_fma_f32 v14, v22, v18, v141
	v_fma_f32 v15, v23, v19, v157
	v_fmac_f32_dpp v12, v16, v24 quad_perm:[1,0,3,2] row_mask:0xf bank_mask:0xf
	v_fmac_f32_dpp v13, v17, v25 quad_perm:[1,0,3,2] row_mask:0xf bank_mask:0xf
	v_fmac_f32_dpp v14, v18, v26 quad_perm:[1,0,3,2] row_mask:0xf bank_mask:0xf
	v_fmac_f32_dpp v15, v19, v27 quad_perm:[1,0,3,2] row_mask:0xf bank_mask:0xf
	v_cvt_pk_f16_f32 v180, v16, v12
	v_cvt_pk_f16_f32 v184, v17, v13
	v_cvt_pk_f16_f32 v188, v18, v14
	v_cvt_pk_f16_f32 v192, v19, v15
	v_fma_f32 v16, v20, v12, v110
	v_fma_f32 v17, v21, v13, v126
	v_fma_f32 v18, v22, v14, v142
	v_fma_f32 v19, v23, v15, v158
	v_fmac_f32_dpp v16, v12, v24 quad_perm:[1,0,3,2] row_mask:0xf bank_mask:0xf
	v_fmac_f32_dpp v17, v13, v25 quad_perm:[1,0,3,2] row_mask:0xf bank_mask:0xf
	v_fmac_f32_dpp v18, v14, v26 quad_perm:[1,0,3,2] row_mask:0xf bank_mask:0xf
	v_fmac_f32_dpp v19, v15, v27 quad_perm:[1,0,3,2] row_mask:0xf bank_mask:0xf
	v_fma_f32 v12, v20, v16, v111
	v_fma_f32 v13, v21, v17, v127
	v_fma_f32 v14, v22, v18, v143
	v_fma_f32 v15, v23, v19, v159
	v_fmac_f32_dpp v12, v16, v24 quad_perm:[1,0,3,2] row_mask:0xf bank_mask:0xf
	v_fmac_f32_dpp v13, v17, v25 quad_perm:[1,0,3,2] row_mask:0xf bank_mask:0xf
	v_fmac_f32_dpp v14, v18, v26 quad_perm:[1,0,3,2] row_mask:0xf bank_mask:0xf
	v_fmac_f32_dpp v15, v19, v27 quad_perm:[1,0,3,2] row_mask:0xf bank_mask:0xf
	v_cvt_pk_f16_f32 v181, v16, v12
	v_cvt_pk_f16_f32 v185, v17, v13
	v_cvt_pk_f16_f32 v189, v18, v14
	v_cvt_pk_f16_f32 v193, v19, v15
	ds_write_b128 v84, v[178:181] offset:4160
	ds_write_b128 v84, v[182:185] offset:4672
	ds_write_b128 v84, v[186:189] offset:5184
	ds_write_b128 v84, v[190:193] offset:5696
	v_add_u32_e32 v93, s79, v87
	ds_read_b64_tr_b16 v[194:195], v85 offset:0
	ds_read_b64_tr_b16 v[196:197], v85 offset:64
	ds_read_b64_tr_b16 v[198:199], v85 offset:512
	ds_read_b64_tr_b16 v[200:201], v85 offset:576
	ds_read_b64_tr_b16 v[206:207], v85 offset:1024
	ds_read_b64_tr_b16 v[208:209], v85 offset:1088
	ds_read_b64_tr_b16 v[210:211], v85 offset:1536
	ds_read_b64_tr_b16 v[212:213], v85 offset:1600
	s_waitcnt lgkmcnt(6)
	v_mfma_f32_16x16x32_f16 v[32:35], v[160:163], v[194:197], 0
	s_waitcnt lgkmcnt(4)
	v_mfma_f32_16x16x32_f16 v[32:35], v[164:167], v[198:201], v[32:35]
	s_waitcnt lgkmcnt(2)
	v_mfma_f32_16x16x32_f16 v[32:35], v[168:171], v[206:209], v[32:35]
	s_waitcnt lgkmcnt(0)
	v_mfma_f32_16x16x32_f16 v[32:35], v[172:175], v[210:213], v[32:35]
	s_nop 7
	s_nop 1
	ds_write_b128 v93, v[32:35] offset:0
	ds_read_b64_tr_b16 v[194:195], v85 offset:2048
	ds_read_b64_tr_b16 v[196:197], v85 offset:2112
	ds_read_b64_tr_b16 v[198:199], v85 offset:2560
	ds_read_b64_tr_b16 v[200:201], v85 offset:2624
	ds_read_b64_tr_b16 v[206:207], v85 offset:3072
	ds_read_b64_tr_b16 v[208:209], v85 offset:3136
	ds_read_b64_tr_b16 v[210:211], v85 offset:3584
	ds_read_b64_tr_b16 v[212:213], v85 offset:3648
	s_waitcnt lgkmcnt(6)
	v_mfma_f32_16x16x32_f16 v[32:35], v[160:163], v[194:197], 0
	s_waitcnt lgkmcnt(4)
	v_mfma_f32_16x16x32_f16 v[32:35], v[164:167], v[198:201], v[32:35]
	s_waitcnt lgkmcnt(2)
	v_mfma_f32_16x16x32_f16 v[32:35], v[168:171], v[206:209], v[32:35]
	s_waitcnt lgkmcnt(0)
	v_mfma_f32_16x16x32_f16 v[32:35], v[172:175], v[210:213], v[32:35]
	s_nop 7
	s_nop 1
	ds_write_b128 v93, v[32:35] offset:4096
	s_waitcnt lgkmcnt(0)
	v_mov_b32_e32 v230, s85
	ds_write_b32 v202, v230
	s_mov_b32 vcc_lo, 0
.Lp8_poll1:
	s_add_u32 vcc_lo, vcc_lo, 1
	s_cmpk_gt_u32 vcc_lo, 0x7d0
	s_cbranch_scc1 .Lp8_poll1_done
	ds_read_b32 v230, v203
	s_waitcnt lgkmcnt(0)
	s_nop 0
	v_readfirstlane_b32 s94, v230
	s_nop 3
	s_cmp_ge_u32 s94, s85
	s_cbranch_scc1 .Lp8_poll1_done
	s_sleep 1
	s_branch .Lp8_poll1
.Lp8_poll1_done:
	s_waitcnt vmcnt(0)
	ds_read_b128 v[96:99], v88 offset:0
	ds_read_b128 v[100:103], v88 offset:16
	ds_read_b128 v[104:107], v88 offset:8192
	ds_read_b128 v[108:111], v88 offset:8208
	ds_read_b128 v[112:115], v88 offset:4096
	ds_read_b128 v[116:119], v88 offset:4112
	ds_read_b128 v[120:123], v88 offset:12288
	ds_read_b128 v[124:127], v88 offset:12304
	s_waitcnt lgkmcnt(4)
	v_add_f32_e32 v128, v96, v104
	v_add_f32_e32 v129, v97, v105
	v_add_f32_e32 v130, v98, v106
	v_add_f32_e32 v131, v99, v107
	v_add_f32_e32 v132, v100, v108
	v_add_f32_e32 v133, v101, v109
	v_add_f32_e32 v134, v102, v110
	v_add_f32_e32 v135, v103, v111
	v_cvt_f32_f16_e32 v144, v214
	v_cvt_f32_f16_sdwa v145, v214 dst_sel:DWORD dst_unused:UNUSED_PAD src0_sel:WORD_1
	v_cvt_f32_f16_e32 v146, v215
	v_cvt_f32_f16_sdwa v147, v215 dst_sel:DWORD dst_unused:UNUSED_PAD src0_sel:WORD_1
	v_cvt_f32_f16_e32 v148, v216
	v_cvt_f32_f16_sdwa v149, v216 dst_sel:DWORD dst_unused:UNUSED_PAD src0_sel:WORD_1
	v_cvt_f32_f16_e32 v150, v217
	v_cvt_f32_f16_sdwa v151, v217 dst_sel:DWORD dst_unused:UNUSED_PAD src0_sel:WORD_1
	v_mul_f32_e32 v144, v144, v222
	v_mul_f32_e32 v145, v145, v223
	v_mul_f32_e32 v146, v146, v224
	v_mul_f32_e32 v147, v147, v225
	v_mul_f32_e32 v148, v148, v226
	v_mul_f32_e32 v149, v149, v227
	v_mul_f32_e32 v150, v150, v228
	v_mul_f32_e32 v151, v151, v229
	v_fma_f32 v136, v128, s81, v144
	v_fma_f32 v137, v129, s81, v145
	v_fma_f32 v138, v130, s81, v146
	v_fma_f32 v139, v131, s81, v147
	v_fma_f32 v140, v132, s81, v148
	v_fma_f32 v141, v133, s81, v149
	v_fma_f32 v142, v134, s81, v150
	v_fma_f32 v143, v135, s81, v151
	v_mul_f32_e32 v144, v136, v136
	v_mul_f32_e32 v145, v137, v137
	v_mul_f32_e32 v146, v138, v138
	v_mul_f32_e32 v147, v139, v139
	v_mul_f32_e32 v148, v140, v140
	v_mul_f32_e32 v149, v141, v141
	v_mul_f32_e32 v150, v142, v142
	v_mul_f32_e32 v151, v143, v143
	v_mul_f32_e32 v144, v144, v136
	v_mul_f32_e32 v145, v145, v137
	v_mul_f32_e32 v146, v146, v138
	v_mul_f32_e32 v147, v147, v139
	v_mul_f32_e32 v148, v148, v140
	v_mul_f32_e32 v149, v149, v141
	v_mul_f32_e32 v150, v150, v142
	v_mul_f32_e32 v151, v151, v143
	v_fma_f32 v144, v144, s82, v136
	v_fma_f32 v145, v145, s82, v137
	v_fma_f32 v146, v146, s82, v138
	v_fma_f32 v147, v147, s82, v139
	v_fma_f32 v148, v148, s82, v140
	v_fma_f32 v149, v149, s82, v141
	v_fma_f32 v150, v150, s82, v142
	v_fma_f32 v151, v151, s82, v143
	v_mul_f32_e32 v144, 0xc0135761, v144
	v_mul_f32_e32 v145, 0xc0135761, v145
	v_mul_f32_e32 v146, 0xc0135761, v146
	v_mul_f32_e32 v147, 0xc0135761, v147
	v_mul_f32_e32 v148, 0xc0135761, v148
	v_mul_f32_e32 v149, 0xc0135761, v149
	v_mul_f32_e32 v150, 0xc0135761, v150
	v_mul_f32_e32 v151, 0xc0135761, v151
	v_exp_f32_e32 v144, v144
	v_exp_f32_e32 v145, v145
	v_exp_f32_e32 v146, v146
	v_exp_f32_e32 v147, v147
	v_exp_f32_e32 v148, v148
	v_exp_f32_e32 v149, v149
	v_exp_f32_e32 v150, v150
	v_exp_f32_e32 v151, v151
	v_add_f32_e32 v144, 1.0, v144
	v_add_f32_e32 v145, 1.0, v145
	v_add_f32_e32 v146, 1.0, v146
	v_add_f32_e32 v147, 1.0, v147
	v_add_f32_e32 v148, 1.0, v148
	v_add_f32_e32 v149, 1.0, v149
	v_add_f32_e32 v150, 1.0, v150
	v_add_f32_e32 v151, 1.0, v151
	v_rcp_f32_e32 v144, v144
	v_rcp_f32_e32 v145, v145
	v_rcp_f32_e32 v146, v146
	v_rcp_f32_e32 v147, v147
	v_rcp_f32_e32 v148, v148
	v_rcp_f32_e32 v149, v149
	v_rcp_f32_e32 v150, v150
	v_rcp_f32_e32 v151, v151
	v_mul_f32_e32 v136, v136, v144
	v_mul_f32_e32 v137, v137, v145
	v_mul_f32_e32 v138, v138, v146
	v_mul_f32_e32 v139, v139, v147
	v_mul_f32_e32 v140, v140, v148
	v_mul_f32_e32 v141, v141, v149
	v_mul_f32_e32 v142, v142, v150
	v_mul_f32_e32 v143, v143, v151
	v_cvt_pk_f16_f32 v152, v136, v137
	v_cvt_pk_f16_f32 v153, v138, v139
	v_cvt_pk_f16_f32 v154, v140, v141
	v_cvt_pk_f16_f32 v155, v142, v143
	global_store_dwordx4 v91, v[152:155], s[74:75]
	s_nop 1
	s_waitcnt lgkmcnt(0)
	v_mov_b32_e32 v230, s85
	ds_write_b32 v202, v230 offset:32
	v_add_f32_e32 v128, v112, v120
	v_add_f32_e32 v129, v113, v121
	v_add_f32_e32 v130, v114, v122
	v_add_f32_e32 v131, v115, v123
	v_add_f32_e32 v132, v116, v124
	v_add_f32_e32 v133, v117, v125
	v_add_f32_e32 v134, v118, v126
	v_add_f32_e32 v135, v119, v127
	v_cvt_f32_f16_e32 v144, v218
	v_cvt_f32_f16_sdwa v145, v218 dst_sel:DWORD dst_unused:UNUSED_PAD src0_sel:WORD_1
	v_cvt_f32_f16_e32 v146, v219
	v_cvt_f32_f16_sdwa v147, v219 dst_sel:DWORD dst_unused:UNUSED_PAD src0_sel:WORD_1
	v_cvt_f32_f16_e32 v148, v220
	v_cvt_f32_f16_sdwa v149, v220 dst_sel:DWORD dst_unused:UNUSED_PAD src0_sel:WORD_1
	v_cvt_f32_f16_e32 v150, v221
	v_cvt_f32_f16_sdwa v151, v221 dst_sel:DWORD dst_unused:UNUSED_PAD src0_sel:WORD_1
	v_mul_f32_e32 v144, v144, v222
	v_mul_f32_e32 v145, v145, v223
	v_mul_f32_e32 v146, v146, v224
	v_mul_f32_e32 v147, v147, v225
	v_mul_f32_e32 v148, v148, v226
	v_mul_f32_e32 v149, v149, v227
	v_mul_f32_e32 v150, v150, v228
	v_mul_f32_e32 v151, v151, v229
	v_fma_f32 v136, v128, s81, v144
	v_fma_f32 v137, v129, s81, v145
	v_fma_f32 v138, v130, s81, v146
	v_fma_f32 v139, v131, s81, v147
	v_fma_f32 v140, v132, s81, v148
	v_fma_f32 v141, v133, s81, v149
	v_fma_f32 v142, v134, s81, v150
	v_fma_f32 v143, v135, s81, v151
	v_mul_f32_e32 v144, v136, v136
	v_mul_f32_e32 v145, v137, v137
	v_mul_f32_e32 v146, v138, v138
	v_mul_f32_e32 v147, v139, v139
	v_mul_f32_e32 v148, v140, v140
	v_mul_f32_e32 v149, v141, v141
	v_mul_f32_e32 v150, v142, v142
	v_mul_f32_e32 v151, v143, v143
	v_mul_f32_e32 v144, v144, v136
	v_mul_f32_e32 v145, v145, v137
	v_mul_f32_e32 v146, v146, v138
	v_mul_f32_e32 v147, v147, v139
	v_mul_f32_e32 v148, v148, v140
	v_mul_f32_e32 v149, v149, v141
	v_mul_f32_e32 v150, v150, v142
	v_mul_f32_e32 v151, v151, v143
	v_fma_f32 v144, v144, s82, v136
	v_fma_f32 v145, v145, s82, v137
	v_fma_f32 v146, v146, s82, v138
	v_fma_f32 v147, v147, s82, v139
	v_fma_f32 v148, v148, s82, v140
	v_fma_f32 v149, v149, s82, v141
	v_fma_f32 v150, v150, s82, v142
	v_fma_f32 v151, v151, s82, v143
	v_mul_f32_e32 v144, 0xc0135761, v144
	v_mul_f32_e32 v145, 0xc0135761, v145
	v_mul_f32_e32 v146, 0xc0135761, v146
	v_mul_f32_e32 v147, 0xc0135761, v147
	v_mul_f32_e32 v148, 0xc0135761, v148
	v_mul_f32_e32 v149, 0xc0135761, v149
	v_mul_f32_e32 v150, 0xc0135761, v150
	v_mul_f32_e32 v151, 0xc0135761, v151
	v_exp_f32_e32 v144, v144
	v_exp_f32_e32 v145, v145
	v_exp_f32_e32 v146, v146
	v_exp_f32_e32 v147, v147
	v_exp_f32_e32 v148, v148
	v_exp_f32_e32 v149, v149
	v_exp_f32_e32 v150, v150
	v_exp_f32_e32 v151, v151
	v_add_f32_e32 v144, 1.0, v144
	v_add_f32_e32 v145, 1.0, v145
	v_add_f32_e32 v146, 1.0, v146
	v_add_f32_e32 v147, 1.0, v147
	v_add_f32_e32 v148, 1.0, v148
	v_add_f32_e32 v149, 1.0, v149
	v_add_f32_e32 v150, 1.0, v150
	v_add_f32_e32 v151, 1.0, v151
	v_rcp_f32_e32 v144, v144
	v_rcp_f32_e32 v145, v145
	v_rcp_f32_e32 v146, v146
	v_rcp_f32_e32 v147, v147
	v_rcp_f32_e32 v148, v148
	v_rcp_f32_e32 v149, v149
	v_rcp_f32_e32 v150, v150
	v_rcp_f32_e32 v151, v151
	v_mul_f32_e32 v136, v136, v144
	v_mul_f32_e32 v137, v137, v145
	v_mul_f32_e32 v138, v138, v146
	v_mul_f32_e32 v139, v139, v147
	v_mul_f32_e32 v140, v140, v148
	v_mul_f32_e32 v141, v141, v149
	v_mul_f32_e32 v142, v142, v150
	v_mul_f32_e32 v143, v143, v151
	v_cvt_pk_f16_f32 v152, v136, v137
	v_cvt_pk_f16_f32 v153, v138, v139
	v_cvt_pk_f16_f32 v154, v140, v141
	v_cvt_pk_f16_f32 v155, v142, v143
	global_store_dwordx4 v92, v[152:155], s[74:75]
	s_nop 1
	s_cmpk_gt_u32 s5, 0x83f
	s_cbranch_scc0 .Lp8_top
